# static priority raise applied to the other wave half (waves 0-3) of the GEMM main loop instead of waves 4-7
# speedup vs baseline: 1.0200x; 1.0200x over previous
; __device__ __forceinline__ void gemm_phase(LAS unsigned char* lds, const GemmD g, const Sched& S, const Epi& E) {
;     ...
;     f32x4 acc[2][2][4][2];
; #pragma unroll
;     for (int a = 0; a < 2; ++a)
; #pragma unroll
;         for (int b = 0; b < 2; ++b)
; #pragma unroll
;             for (int m = 0; m < 4; ++m)
; #pragma unroll
;                 for (int n = 0; n < 2; ++n) acc[a][b][m][n] = (f32x4){0.f, 0.f, 0.f, 0.f};
.LBB0_214:
	s_add_u32 s8, s8, 0x80
	s_addc_u32 s9, s9, 0
	s_add_u32 s34, s26, 0x100
	v_mov_b32_e32 v2, 0
	s_addc_u32 s35, s27, 0
	s_mov_b32 s26, 0
	v_mov_b32_e32 v3, v2
	v_mov_b32_e32 v4, v2
	v_mov_b32_e32 v5, v2
	v_mov_b32_e32 v6, v2
	v_mov_b32_e32 v7, v2
	v_mov_b32_e32 v8, v2
	v_mov_b32_e32 v9, v2
	v_mov_b32_e32 v18, v2
	v_mov_b32_e32 v19, v2
	v_mov_b32_e32 v20, v2
	v_mov_b32_e32 v21, v2
	v_mov_b32_e32 v22, v2
	v_mov_b32_e32 v23, v2
	v_mov_b32_e32 v24, v2
	v_mov_b32_e32 v25, v2
	v_mov_b32_e32 v34, v2
	v_mov_b32_e32 v35, v2
	v_mov_b32_e32 v36, v2
	v_mov_b32_e32 v37, v2
	v_mov_b32_e32 v38, v2
	v_mov_b32_e32 v39, v2
	v_mov_b32_e32 v40, v2
	v_mov_b32_e32 v41, v2
	v_mov_b32_e32 v50, v2
	v_mov_b32_e32 v51, v2
	v_mov_b32_e32 v52, v2
	v_mov_b32_e32 v53, v2
	v_mov_b32_e32 v54, v2
	v_mov_b32_e32 v55, v2
	v_mov_b32_e32 v56, v2
	v_mov_b32_e32 v57, v2
	v_mov_b32_e32 v10, v2
	v_mov_b32_e32 v11, v2
	v_mov_b32_e32 v12, v2
	v_mov_b32_e32 v13, v2
	v_mov_b32_e32 v14, v2
	v_mov_b32_e32 v15, v2
	v_mov_b32_e32 v16, v2
	v_mov_b32_e32 v17, v2
	v_mov_b32_e32 v26, v2
	v_mov_b32_e32 v27, v2
	v_mov_b32_e32 v28, v2
	v_mov_b32_e32 v29, v2
	v_mov_b32_e32 v30, v2
	v_mov_b32_e32 v31, v2
	v_mov_b32_e32 v32, v2
	v_mov_b32_e32 v33, v2
	v_mov_b32_e32 v42, v2
	v_mov_b32_e32 v43, v2
	v_mov_b32_e32 v44, v2
	v_mov_b32_e32 v45, v2
	v_mov_b32_e32 v46, v2
	v_mov_b32_e32 v47, v2
	v_mov_b32_e32 v48, v2
	v_mov_b32_e32 v49, v2
	v_mov_b32_e32 v58, v2
	v_mov_b32_e32 v59, v2
	v_mov_b32_e32 v60, v2
	v_mov_b32_e32 v61, v2
	v_mov_b32_e32 v62, v2
	v_mov_b32_e32 v63, v2
	v_mov_b32_e32 v64, v2
	v_mov_b32_e32 v65, v2
	v_mov_b32_e32 v66, v2
	v_mov_b32_e32 v67, v2
	v_mov_b32_e32 v68, v2
	v_mov_b32_e32 v69, v2
	v_mov_b32_e32 v70, v2
	v_mov_b32_e32 v71, v2
	v_mov_b32_e32 v72, v2
	v_mov_b32_e32 v73, v2
	v_mov_b32_e32 v82, v2
	v_mov_b32_e32 v83, v2
	v_mov_b32_e32 v84, v2
	v_mov_b32_e32 v85, v2
	v_mov_b32_e32 v86, v2
	v_mov_b32_e32 v87, v2
	v_mov_b32_e32 v88, v2
	v_mov_b32_e32 v89, v2
	v_mov_b32_e32 v98, v2
	v_mov_b32_e32 v99, v2
	v_mov_b32_e32 v100, v2
	v_mov_b32_e32 v101, v2
	v_mov_b32_e32 v102, v2
	v_mov_b32_e32 v103, v2
	v_mov_b32_e32 v104, v2
	v_mov_b32_e32 v105, v2
	v_mov_b32_e32 v114, v2
	v_mov_b32_e32 v115, v2
	v_mov_b32_e32 v116, v2
	v_mov_b32_e32 v117, v2
	v_mov_b32_e32 v118, v2
	v_mov_b32_e32 v119, v2
	v_mov_b32_e32 v120, v2
	v_mov_b32_e32 v121, v2
	v_mov_b32_e32 v74, v2
	v_mov_b32_e32 v75, v2
	v_mov_b32_e32 v76, v2
	v_mov_b32_e32 v77, v2
	v_mov_b32_e32 v78, v2
	v_mov_b32_e32 v79, v2
	v_mov_b32_e32 v80, v2
	v_mov_b32_e32 v81, v2
	v_mov_b32_e32 v90, v2
	v_mov_b32_e32 v91, v2
	v_mov_b32_e32 v92, v2
	v_mov_b32_e32 v93, v2
	v_mov_b32_e32 v94, v2
	v_mov_b32_e32 v95, v2
	v_mov_b32_e32 v96, v2
	v_mov_b32_e32 v97, v2
	v_mov_b32_e32 v106, v2
	v_mov_b32_e32 v107, v2
	v_mov_b32_e32 v108, v2
	v_mov_b32_e32 v109, v2
	v_mov_b32_e32 v110, v2
	v_mov_b32_e32 v111, v2
	v_mov_b32_e32 v112, v2
	v_mov_b32_e32 v113, v2
	v_mov_b32_e32 v122, v2
	v_mov_b32_e32 v123, v2
	v_mov_b32_e32 v124, v2
	v_mov_b32_e32 v125, v2
	v_mov_b32_e32 v126, v2
	v_mov_b32_e32 v127, v2
	v_mov_b32_e32 v128, v2
	v_mov_b32_e32 v129, v2
	v_readlane_b32 s22, v250, 17
	s_cmp_lg_u32 s22, 0
	s_cbranch_scc1 .Lprio_done
	s_setprio 1
